# attention softmax (MLA, DSA, diff): s-m on register pairs by one v_pk_add_f32 with negated broadcast m instead of two v_sub_f32
# baseline (speedup 1.0000x reference)
; __device__ __forceinline__ unsigned cvtpk(float lo, float hi) { unsigned r; asm("v_cvt_pk_bf16_f32 %0, %1, %2" : "=v"(r) : "v"(lo), "v"(hi)); return r; }
; __device__ __forceinline__ float max_x32(float v) { const unsigned u = __float_as_uint(v); auto r = __builtin_amdgcn_permlane32_swap(u, u, false, false); return fmaxf(__uint_as_float(r[0]), __uint_as_float(r[1])); }
; template <bool MASKED>
; __device__ __forceinline__ void softmax_tile(f32x16& s0, f32x16& s1, float& m, float& l, float& alpha, unsigned mlo, unsigned mhi, bf16x8 (&pk)[4]) {
;     ...
;     float mx = fmaxf(s0[0], s1[0]);
; #pragma unroll
;     for (int r = 1; r < 16; ++r) mx = fmaxf(mx, fmaxf(s0[r], s1[r]));
;     mx = max_x32(mx);
;     const float mn = fmaxf(m, mx);
;     alpha = __builtin_amdgcn_exp2f(m - mn); m = mn;
;     float sum = 0.f;
; #pragma unroll
;     for (int r = 0; r < 16; ++r) {
;         float p0 = __builtin_amdgcn_exp2f(s0[r] - mn), p1 = __builtin_amdgcn_exp2f(s1[r] - mn);
;         if (MASKED) { if (s0[r] <= -1e29f) p0 = 0.f; if (s1[r] <= -1e29f) p1 = 0.f; }
;         s0[r] = p0; s1[r] = p1; sum += p0 + p1;
;     }
;     l = l * alpha + sum;
; #pragma unroll
;     for (int k2 = 0; k2 < 2; ++k2) {
;         u32x4 a, b;
;         a.x = cvtpk(s0[8 * k2 + 0], s0[8 * k2 + 1]); a.y = cvtpk(s0[8 * k2 + 2], s0[8 * k2 + 3]); a.z = cvtpk(s0[8 * k2 + 4], s0[8 * k2 + 5]); a.w = cvtpk(s0[8 * k2 + 6], s0[8 * k2 + 7]);
;         b.x = cvtpk(s1[8 * k2 + 0], s1[8 * k2 + 1]); b.y = cvtpk(s1[8 * k2 + 2], s1[8 * k2 + 3]); b.z = cvtpk(s1[8 * k2 + 4], s1[8 * k2 + 5]); b.w = cvtpk(s1[8 * k2 + 6], s1[8 * k2 + 7]);
;         pk[k2] = __builtin_bit_cast(bf16x8, a); pk[2 + k2] = __builtin_bit_cast(bf16x8, b);
;     }
.LBB0_626:
	s_cmp_gt_i32 s7, s25
	s_cbranch_scc1 .LBB0_630
	s_mul_i32 s26, s17, 0xa000
	s_add_i32 s26, s26, 0
	v_add_u32_e32 v0, s26, v124
	v_add_u32_e32 v70, v0, v126
	v_add_u32_e32 v74, v0, v127
	ds_read_b128 v[66:69], v70
	ds_read_b128 v[70:73], v70 offset:8192
	ds_read_b128 v[150:153], v74
	ds_read_b128 v[154:157], v74 offset:8192
	v_add_u32_e32 v74, v0, v128
	v_add_u32_e32 v0, v0, v129
	ds_read_b128 v[158:161], v74
	ds_read_b128 v[162:165], v74 offset:8192
	ds_read_b128 v[166:169], v0
	ds_read_b128 v[170:173], v0 offset:8192
	s_waitcnt lgkmcnt(0)
	v_mfma_f32_32x32x16_bf16 v[82:97], v[66:69], v[98:101], 0
	v_mfma_f32_32x32x16_bf16 v[66:81], v[70:73], v[98:101], 0
	v_mfma_f32_32x32x16_bf16 v[82:97], v[150:153], v[102:105], v[82:97]
	v_mfma_f32_32x32x16_bf16 v[66:81], v[154:157], v[102:105], v[66:81]
	v_mfma_f32_32x32x16_bf16 v[82:97], v[158:161], v[106:109], v[82:97]
	v_mfma_f32_32x32x16_bf16 v[66:81], v[162:165], v[106:109], v[66:81]
	v_mfma_f32_32x32x16_bf16 v[82:97], v[166:169], v[110:113], v[82:97]
	v_mfma_f32_32x32x16_bf16 v[66:81], v[170:173], v[110:113], v[66:81]
	s_nop 11
	v_max3_f32 v150, v82, v83, v84
	v_max3_f32 v151, v85, v86, v87
	v_max3_f32 v152, v88, v89, v90
	v_max3_f32 v153, v91, v92, v93
	v_max3_f32 v154, v94, v95, v96
	v_max3_f32 v155, v97, v66, v67
	v_max3_f32 v156, v68, v69, v70
	v_max3_f32 v157, v71, v72, v73
	v_max3_f32 v158, v74, v75, v76
	v_max3_f32 v159, v77, v78, v79
	v_max3_f32 v150, v150, v151, v152
	v_max3_f32 v153, v153, v154, v155
	v_max3_f32 v156, v156, v157, v158
	v_max3_f32 v159, v159, v80, v81
	v_max3_f32 v150, v150, v153, v156
	v_max_f32_e32 v150, v150, v159
	v_mov_b32_e32 v151, v150
	s_nop 1
	v_permlane32_swap_b32_e32 v150, v151
	v_max3_f32 v146, v148, v150, v151
	v_sub_f32_e32 v0, v148, v146
	v_pk_add_f32 v[82:83], v[82:83], v[146:147] op_sel_hi:[1,0] neg_lo:[0,1] neg_hi:[0,1]
	v_pk_add_f32 v[84:85], v[84:85], v[146:147] op_sel_hi:[1,0] neg_lo:[0,1] neg_hi:[0,1]
	v_pk_add_f32 v[86:87], v[86:87], v[146:147] op_sel_hi:[1,0] neg_lo:[0,1] neg_hi:[0,1]
	v_pk_add_f32 v[88:89], v[88:89], v[146:147] op_sel_hi:[1,0] neg_lo:[0,1] neg_hi:[0,1]
	v_pk_add_f32 v[90:91], v[90:91], v[146:147] op_sel_hi:[1,0] neg_lo:[0,1] neg_hi:[0,1]
	v_pk_add_f32 v[92:93], v[92:93], v[146:147] op_sel_hi:[1,0] neg_lo:[0,1] neg_hi:[0,1]
	v_pk_add_f32 v[94:95], v[94:95], v[146:147] op_sel_hi:[1,0] neg_lo:[0,1] neg_hi:[0,1]
	v_pk_add_f32 v[96:97], v[96:97], v[146:147] op_sel_hi:[1,0] neg_lo:[0,1] neg_hi:[0,1]
	v_pk_add_f32 v[66:67], v[66:67], v[146:147] op_sel_hi:[1,0] neg_lo:[0,1] neg_hi:[0,1]
	v_pk_add_f32 v[68:69], v[68:69], v[146:147] op_sel_hi:[1,0] neg_lo:[0,1] neg_hi:[0,1]
	v_pk_add_f32 v[70:71], v[70:71], v[146:147] op_sel_hi:[1,0] neg_lo:[0,1] neg_hi:[0,1]
	v_pk_add_f32 v[72:73], v[72:73], v[146:147] op_sel_hi:[1,0] neg_lo:[0,1] neg_hi:[0,1]
	v_pk_add_f32 v[74:75], v[74:75], v[146:147] op_sel_hi:[1,0] neg_lo:[0,1] neg_hi:[0,1]
	v_pk_add_f32 v[76:77], v[76:77], v[146:147] op_sel_hi:[1,0] neg_lo:[0,1] neg_hi:[0,1]
	v_pk_add_f32 v[78:79], v[78:79], v[146:147] op_sel_hi:[1,0] neg_lo:[0,1] neg_hi:[0,1]
	v_pk_add_f32 v[80:81], v[80:81], v[146:147] op_sel_hi:[1,0] neg_lo:[0,1] neg_hi:[0,1]
	v_exp_f32_e32 v0, v0
	v_exp_f32_e32 v82, v82
	v_exp_f32_e32 v83, v83
	v_exp_f32_e32 v84, v84
	v_exp_f32_e32 v85, v85
	v_exp_f32_e32 v86, v86
	v_exp_f32_e32 v87, v87
	v_exp_f32_e32 v88, v88
	v_exp_f32_e32 v89, v89
	v_exp_f32_e32 v90, v90
	v_exp_f32_e32 v91, v91
	v_exp_f32_e32 v92, v92
	v_exp_f32_e32 v93, v93
	v_exp_f32_e32 v94, v94
	v_exp_f32_e32 v95, v95
	v_exp_f32_e32 v96, v96
	v_exp_f32_e32 v97, v97
	v_exp_f32_e32 v66, v66
	v_exp_f32_e32 v67, v67
	v_exp_f32_e32 v68, v68
	v_exp_f32_e32 v69, v69
	v_exp_f32_e32 v70, v70
	v_exp_f32_e32 v71, v71
	v_exp_f32_e32 v72, v72
	v_exp_f32_e32 v73, v73
	v_exp_f32_e32 v74, v74
	v_exp_f32_e32 v75, v75
	v_exp_f32_e32 v76, v76
	v_exp_f32_e32 v77, v77
	v_exp_f32_e32 v78, v78
	v_exp_f32_e32 v79, v79
	v_exp_f32_e32 v80, v80
	v_exp_f32_e32 v81, v81
	v_pk_add_f32 v[150:151], v[82:83], v[84:85]
	v_pk_add_f32 v[152:153], v[86:87], v[88:89]
	v_pk_add_f32 v[154:155], v[90:91], v[92:93]
	v_pk_add_f32 v[156:157], v[94:95], v[96:97]
	v_pk_add_f32 v[158:159], v[66:67], v[68:69]
	v_pk_add_f32 v[160:161], v[70:71], v[72:73]
	v_pk_add_f32 v[162:163], v[74:75], v[76:77]
	v_pk_add_f32 v[164:165], v[78:79], v[80:81]
	v_pk_add_f32 v[150:151], v[150:151], v[152:153]
	v_pk_add_f32 v[154:155], v[154:155], v[156:157]
	v_pk_add_f32 v[158:159], v[158:159], v[160:161]
	v_pk_add_f32 v[162:163], v[162:163], v[164:165]
	v_pk_add_f32 v[150:151], v[150:151], v[154:155]
	v_pk_add_f32 v[158:159], v[158:159], v[162:163]
	v_pk_add_f32 v[150:151], v[150:151], v[158:159]
	v_add_f32_e32 v164, v150, v151
	v_cvt_pk_bf16_f32 v66, v66, v67
	v_cvt_pk_bf16_f32 v67, v68, v69
	v_cvt_pk_bf16_f32 v68, v70, v71
	v_cvt_pk_bf16_f32 v69, v72, v73
	v_cvt_pk_bf16_f32 v70, v74, v75
	v_cvt_pk_bf16_f32 v71, v76, v77
	v_cvt_pk_bf16_f32 v72, v78, v79
	v_cvt_pk_bf16_f32 v73, v80, v81
	v_cvt_pk_bf16_f32 v74, v82, v83
	v_cvt_pk_bf16_f32 v75, v84, v85
	v_cvt_pk_bf16_f32 v76, v86, v87
	v_cvt_pk_bf16_f32 v77, v88, v89
	v_cvt_pk_bf16_f32 v78, v90, v91
	v_cvt_pk_bf16_f32 v79, v92, v93
	v_cvt_pk_bf16_f32 v80, v94, v95
	v_cvt_pk_bf16_f32 v81, v96, v97
	v_fmac_f32_e32 v164, v147, v0
	v_cmp_neq_f32_e32 vcc, 1.0, v0
	s_cbranch_vccz .LBB0_629
	v_pk_mul_f32 v[64:65], v[64:65], v[0:1] op_sel_hi:[1,0]
	v_pk_mul_f32 v[62:63], v[62:63], v[0:1] op_sel_hi:[1,0]
	v_pk_mul_f32 v[60:61], v[60:61], v[0:1] op_sel_hi:[1,0]
	v_pk_mul_f32 v[58:59], v[58:59], v[0:1] op_sel_hi:[1,0]
	v_pk_mul_f32 v[56:57], v[56:57], v[0:1] op_sel_hi:[1,0]
	v_pk_mul_f32 v[54:55], v[54:55], v[0:1] op_sel_hi:[1,0]
	v_pk_mul_f32 v[52:53], v[52:53], v[0:1] op_sel_hi:[1,0]
	v_pk_mul_f32 v[50:51], v[50:51], v[0:1] op_sel_hi:[1,0]
	v_pk_mul_f32 v[48:49], v[48:49], v[0:1] op_sel_hi:[1,0]
	v_pk_mul_f32 v[46:47], v[46:47], v[0:1] op_sel_hi:[1,0]
	v_pk_mul_f32 v[44:45], v[44:45], v[0:1] op_sel_hi:[1,0]
	v_pk_mul_f32 v[42:43], v[42:43], v[0:1] op_sel_hi:[1,0]
	v_pk_mul_f32 v[40:41], v[40:41], v[0:1] op_sel_hi:[1,0]
	v_pk_mul_f32 v[38:39], v[38:39], v[0:1] op_sel_hi:[1,0]
	v_pk_mul_f32 v[36:37], v[36:37], v[0:1] op_sel_hi:[1,0]
	v_pk_mul_f32 v[34:35], v[34:35], v[0:1] op_sel_hi:[1,0]
	v_pk_mul_f32 v[32:33], v[32:33], v[0:1] op_sel_hi:[1,0]
	v_pk_mul_f32 v[30:31], v[30:31], v[0:1] op_sel_hi:[1,0]
	v_pk_mul_f32 v[28:29], v[28:29], v[0:1] op_sel_hi:[1,0]
	v_pk_mul_f32 v[26:27], v[26:27], v[0:1] op_sel_hi:[1,0]
	v_pk_mul_f32 v[24:25], v[24:25], v[0:1] op_sel_hi:[1,0]
	v_pk_mul_f32 v[22:23], v[22:23], v[0:1] op_sel_hi:[1,0]
	v_pk_mul_f32 v[20:21], v[20:21], v[0:1] op_sel_hi:[1,0]
	v_pk_mul_f32 v[18:19], v[18:19], v[0:1] op_sel_hi:[1,0]
	v_pk_mul_f32 v[16:17], v[16:17], v[0:1] op_sel_hi:[1,0]
	v_pk_mul_f32 v[14:15], v[14:15], v[0:1] op_sel_hi:[1,0]
	v_pk_mul_f32 v[12:13], v[12:13], v[0:1] op_sel_hi:[1,0]
	v_pk_mul_f32 v[10:11], v[10:11], v[0:1] op_sel_hi:[1,0]
	v_pk_mul_f32 v[8:9], v[8:9], v[0:1] op_sel_hi:[1,0]
	v_pk_mul_f32 v[6:7], v[6:7], v[0:1] op_sel_hi:[1,0]
	v_pk_mul_f32 v[4:5], v[4:5], v[0:1] op_sel_hi:[1,0]
	v_pk_mul_f32 v[2:3], v[2:3], v[0:1] op_sel_hi:[1,0]

; __device__ __forceinline__ float max_x32(float v) { const unsigned u = __float_as_uint(v); auto r = __builtin_amdgcn_permlane32_swap(u, u, false, false); return fmaxf(__uint_as_float(r[0]), __uint_as_float(r[1])); }
; template <bool MASKED>
; __device__ __forceinline__ void softmax_tile(f32x16& s0, f32x16& s1, float& m, float& l, float& alpha, unsigned mlo, unsigned mhi, bf16x8 (&pk)[4]) {
;     ...
;         for (int r = 0; r < 16; ++r) { const int bit = (r & 3) + 8 * (r >> 2); if (!((mlo >> bit) & 1u)) s0[r] = NEG; if (!((mhi >> bit) & 1u)) s1[r] = NEG; }
;     }
;     float mx = fmaxf(s0[0], s1[0]);
; #pragma unroll
;     for (int r = 1; r < 16; ++r) mx = fmaxf(mx, fmaxf(s0[r], s1[r]));
;     mx = max_x32(mx);
;     const float mn = fmaxf(m, mx);
.LBB0_1176:
	s_andn2_b64 vcc, exec, s[12:13]
	s_cbranch_vccnz .LBB0_1180
	s_mul_i32 s12, s17, 0xa000
	s_add_i32 s12, s12, 0
	v_add_u32_e32 v194, s12, v141
	v_add_u32_e32 v70, v194, v143
	v_add_u32_e32 v74, v194, v144
	ds_read_b128 v[66:69], v70
	ds_read_b128 v[70:73], v70 offset:8192
	ds_read_b128 v[160:163], v74
	ds_read_b128 v[164:167], v74 offset:8192
	v_add_u32_e32 v74, v194, v145
	ds_read_b128 v[168:171], v74
	ds_read_b128 v[172:175], v74 offset:8192
	v_add_u32_e32 v74, v194, v146
	ds_read_b128 v[186:189], v74 offset:8192
	ds_read_b128 v[190:193], v74
	s_waitcnt lgkmcnt(0)
	v_mfma_f32_32x32x16_bf16 v[82:97], v[66:69], v[98:101], 0
	v_mfma_f32_32x32x16_bf16 v[66:81], v[70:73], v[98:101], 0
	v_mfma_f32_32x32x16_bf16 v[82:97], v[160:163], v[102:105], v[82:97]
	v_mfma_f32_32x32x16_bf16 v[66:81], v[164:167], v[102:105], v[66:81]
	v_mfma_f32_32x32x16_bf16 v[82:97], v[168:171], v[106:109], v[82:97]
	v_mfma_f32_32x32x16_bf16 v[66:81], v[172:175], v[106:109], v[66:81]
	v_mfma_f32_32x32x16_bf16 v[82:97], v[190:193], v[110:113], v[82:97]
	v_mfma_f32_32x32x16_bf16 v[66:81], v[186:189], v[110:113], v[66:81]
	v_add_u32_e32 v164, v194, v147
	v_add_u32_e32 v172, v194, v148
	v_add_u32_e32 v190, v194, v149
	v_add_u32_e32 v198, v194, v150
	ds_read_b128 v[160:163], v164
	ds_read_b128 v[164:167], v164 offset:8192
	ds_read_b128 v[168:171], v172
	ds_read_b128 v[172:175], v172 offset:8192
	ds_read_b128 v[186:189], v190
	ds_read_b128 v[190:193], v190 offset:8192
	ds_read_b128 v[194:197], v198 offset:8192
	ds_read_b128 v[206:209], v198
	s_waitcnt lgkmcnt(0)
	v_mfma_f32_32x32x16_bf16 v[82:97], v[160:163], v[114:117], v[82:97]
	v_mfma_f32_32x32x16_bf16 v[66:81], v[164:167], v[114:117], v[66:81]
	v_mfma_f32_32x32x16_bf16 v[82:97], v[168:171], v[118:121], v[82:97]
	v_mfma_f32_32x32x16_bf16 v[66:81], v[172:175], v[118:121], v[66:81]
	v_mfma_f32_32x32x16_bf16 v[82:97], v[186:189], v[122:125], v[82:97]
	v_mfma_f32_32x32x16_bf16 v[66:81], v[190:193], v[122:125], v[66:81]
	v_mfma_f32_32x32x16_bf16 v[82:97], v[206:209], v[126:129], v[82:97]
	v_mfma_f32_32x32x16_bf16 v[66:81], v[194:197], v[126:129], v[66:81]
	v_bfe_i32 v160, v185, 0, 1
	v_bfe_i32 v161, v185, 1, 1
	v_bfe_i32 v162, v185, 2, 1
	v_bfe_i32 v163, v185, 3, 1
	v_bfe_i32 v164, v185, 8, 1
	v_bfe_i32 v165, v185, 9, 1
	v_bfe_i32 v166, v185, 10, 1
	v_bfe_i32 v167, v185, 11, 1
	v_bfe_i32 v168, v185, 16, 1
	v_bfe_i32 v169, v185, 17, 1
	v_bfe_i32 v170, v185, 18, 1
	v_bfe_i32 v171, v185, 19, 1
	v_bfe_i32 v172, v185, 24, 1
	v_bfe_i32 v173, v185, 25, 1
	v_bfe_i32 v174, v185, 26, 1
	v_bfe_i32 v175, v185, 27, 1
	v_bfe_i32 v186, v0, 0, 1
	v_bfe_i32 v187, v0, 1, 1
	v_bfe_i32 v188, v0, 2, 1
	v_bfe_i32 v189, v0, 3, 1
	v_bfe_i32 v190, v0, 8, 1
	v_bfe_i32 v191, v0, 9, 1
	v_bfe_i32 v192, v0, 10, 1
	v_bfe_i32 v193, v0, 11, 1
	v_bfe_i32 v194, v0, 16, 1
	v_bfe_i32 v195, v0, 17, 1
	v_bfe_i32 v196, v0, 18, 1
	v_bfe_i32 v197, v0, 19, 1
	v_bfe_i32 v198, v0, 24, 1
	v_bfe_i32 v199, v0, 25, 1
	v_bfe_i32 v206, v0, 26, 1
	v_bfe_i32 v207, v0, 27, 1
	v_bfi_b32 v82, v160, v82, v215
	v_bfi_b32 v83, v161, v83, v215
	v_bfi_b32 v84, v162, v84, v215
	v_bfi_b32 v85, v163, v85, v215
	v_bfi_b32 v86, v164, v86, v215
	v_bfi_b32 v87, v165, v87, v215
	v_bfi_b32 v88, v166, v88, v215
	v_bfi_b32 v89, v167, v89, v215
	v_bfi_b32 v90, v168, v90, v215
	v_bfi_b32 v91, v169, v91, v215
	v_bfi_b32 v92, v170, v92, v215
	v_bfi_b32 v93, v171, v93, v215
	v_bfi_b32 v94, v172, v94, v215
	v_bfi_b32 v95, v173, v95, v215
	v_bfi_b32 v96, v174, v96, v215
	v_bfi_b32 v97, v175, v97, v215
	v_bfi_b32 v66, v186, v66, v215
	v_bfi_b32 v67, v187, v67, v215
	v_bfi_b32 v68, v188, v68, v215
	v_bfi_b32 v69, v189, v69, v215
	v_bfi_b32 v70, v190, v70, v215
	v_bfi_b32 v71, v191, v71, v215
	v_bfi_b32 v72, v192, v72, v215
	v_bfi_b32 v73, v193, v73, v215
	v_bfi_b32 v74, v194, v74, v215
	v_bfi_b32 v75, v195, v75, v215
	v_bfi_b32 v76, v196, v76, v215
	v_bfi_b32 v77, v197, v77, v215
	v_bfi_b32 v78, v198, v78, v215
	v_bfi_b32 v79, v199, v79, v215
	v_bfi_b32 v80, v206, v80, v215
	v_bfi_b32 v81, v207, v81, v215
	v_max3_f32 v160, v82, v83, v84
	v_max3_f32 v161, v85, v86, v87
	v_max3_f32 v162, v88, v89, v90
	v_max3_f32 v163, v91, v92, v93
	v_max3_f32 v164, v94, v95, v96
	v_max3_f32 v165, v97, v66, v67
	v_max3_f32 v166, v68, v69, v70
	v_max3_f32 v167, v71, v72, v73
	v_max3_f32 v168, v74, v75, v76
	v_max3_f32 v169, v77, v78, v79
	v_max3_f32 v160, v160, v161, v162
	v_max3_f32 v163, v163, v164, v165
	v_max3_f32 v166, v166, v167, v168
	v_max3_f32 v169, v169, v80, v81
	v_max3_f32 v160, v160, v163, v166
	v_max_f32_e32 v160, v160, v169
	v_mov_b32_e32 v161, v160
	s_nop 1
	v_permlane32_swap_b32_e32 v160, v161
	v_max3_f32 v162, v184, v160, v161
	v_max_f32_e32 v162, s97, v162
	v_sub_f32_e32 v0, v184, v162
	v_pk_add_f32 v[82:83], v[82:83], v[162:163] op_sel_hi:[1,0] neg_lo:[0,1] neg_hi:[0,1]
	v_pk_add_f32 v[84:85], v[84:85], v[162:163] op_sel_hi:[1,0] neg_lo:[0,1] neg_hi:[0,1]
	v_pk_add_f32 v[86:87], v[86:87], v[162:163] op_sel_hi:[1,0] neg_lo:[0,1] neg_hi:[0,1]
	v_pk_add_f32 v[88:89], v[88:89], v[162:163] op_sel_hi:[1,0] neg_lo:[0,1] neg_hi:[0,1]
; __device__ __forceinline__ unsigned cvtpk(float lo, float hi) { unsigned r; asm("v_cvt_pk_bf16_f32 %0, %1, %2" : "=v"(r) : "v"(lo), "v"(hi)); return r; }
; template <bool MASKED>
; __device__ __forceinline__ void softmax_tile(f32x16& s0, f32x16& s1, float& m, float& l, float& alpha, unsigned mlo, unsigned mhi, bf16x8 (&pk)[4]) {
;     ...
;     const float mn = fmaxf(m, mx);
;     alpha = __builtin_amdgcn_exp2f(m - mn); m = mn;
;     float sum = 0.f;
; #pragma unroll
;     for (int r = 0; r < 16; ++r) {
;         float p0 = __builtin_amdgcn_exp2f(s0[r] - mn), p1 = __builtin_amdgcn_exp2f(s1[r] - mn);
;         if (MASKED) { if (s0[r] <= -1e29f) p0 = 0.f; if (s1[r] <= -1e29f) p1 = 0.f; }
;         s0[r] = p0; s1[r] = p1; sum += p0 + p1;
;     }
;     l = l * alpha + sum;
; #pragma unroll
;     for (int k2 = 0; k2 < 2; ++k2) {
;         u32x4 a, b;
;         a.x = cvtpk(s0[8 * k2 + 0], s0[8 * k2 + 1]); a.y = cvtpk(s0[8 * k2 + 2], s0[8 * k2 + 3]); a.z = cvtpk(s0[8 * k2 + 4], s0[8 * k2 + 5]); a.w = cvtpk(s0[8 * k2 + 6], s0[8 * k2 + 7]);
;         b.x = cvtpk(s1[8 * k2 + 0], s1[8 * k2 + 1]); b.y = cvtpk(s1[8 * k2 + 2], s1[8 * k2 + 3]); b.z = cvtpk(s1[8 * k2 + 4], s1[8 * k2 + 5]); b.w = cvtpk(s1[8 * k2 + 6], s1[8 * k2 + 7]);
;         pk[k2] = __builtin_bit_cast(bf16x8, a); pk[2 + k2] = __builtin_bit_cast(bf16x8, b);
;     }
	v_pk_add_f32 v[90:91], v[90:91], v[162:163] op_sel_hi:[1,0] neg_lo:[0,1] neg_hi:[0,1]
	v_pk_add_f32 v[92:93], v[92:93], v[162:163] op_sel_hi:[1,0] neg_lo:[0,1] neg_hi:[0,1]
	v_pk_add_f32 v[94:95], v[94:95], v[162:163] op_sel_hi:[1,0] neg_lo:[0,1] neg_hi:[0,1]
	v_pk_add_f32 v[96:97], v[96:97], v[162:163] op_sel_hi:[1,0] neg_lo:[0,1] neg_hi:[0,1]
	v_pk_add_f32 v[66:67], v[66:67], v[162:163] op_sel_hi:[1,0] neg_lo:[0,1] neg_hi:[0,1]
	v_pk_add_f32 v[68:69], v[68:69], v[162:163] op_sel_hi:[1,0] neg_lo:[0,1] neg_hi:[0,1]
	v_pk_add_f32 v[70:71], v[70:71], v[162:163] op_sel_hi:[1,0] neg_lo:[0,1] neg_hi:[0,1]
	v_pk_add_f32 v[72:73], v[72:73], v[162:163] op_sel_hi:[1,0] neg_lo:[0,1] neg_hi:[0,1]
	v_pk_add_f32 v[74:75], v[74:75], v[162:163] op_sel_hi:[1,0] neg_lo:[0,1] neg_hi:[0,1]
	v_pk_add_f32 v[76:77], v[76:77], v[162:163] op_sel_hi:[1,0] neg_lo:[0,1] neg_hi:[0,1]
	v_pk_add_f32 v[78:79], v[78:79], v[162:163] op_sel_hi:[1,0] neg_lo:[0,1] neg_hi:[0,1]
	v_pk_add_f32 v[80:81], v[80:81], v[162:163] op_sel_hi:[1,0] neg_lo:[0,1] neg_hi:[0,1]
	v_exp_f32_e32 v0, v0
	v_exp_f32_e32 v82, v82
	v_exp_f32_e32 v83, v83
	v_exp_f32_e32 v84, v84
	v_exp_f32_e32 v85, v85
	v_exp_f32_e32 v86, v86
	v_exp_f32_e32 v87, v87
	v_exp_f32_e32 v88, v88
	v_exp_f32_e32 v89, v89
	v_exp_f32_e32 v90, v90
	v_exp_f32_e32 v91, v91
	v_exp_f32_e32 v92, v92
	v_exp_f32_e32 v93, v93
	v_exp_f32_e32 v94, v94
	v_exp_f32_e32 v95, v95
	v_exp_f32_e32 v96, v96
	v_exp_f32_e32 v97, v97
	v_exp_f32_e32 v66, v66
	v_exp_f32_e32 v67, v67
	v_exp_f32_e32 v68, v68
	v_exp_f32_e32 v69, v69
	v_exp_f32_e32 v70, v70
	v_exp_f32_e32 v71, v71
	v_exp_f32_e32 v72, v72
	v_exp_f32_e32 v73, v73
	v_exp_f32_e32 v74, v74
	v_exp_f32_e32 v75, v75
	v_exp_f32_e32 v76, v76
	v_exp_f32_e32 v77, v77
	v_exp_f32_e32 v78, v78
	v_exp_f32_e32 v79, v79
	v_exp_f32_e32 v80, v80
	v_exp_f32_e32 v81, v81
	v_pk_add_f32 v[164:165], v[82:83], v[84:85]
	v_pk_add_f32 v[166:167], v[86:87], v[88:89]
	v_pk_add_f32 v[168:169], v[90:91], v[92:93]
	v_pk_add_f32 v[170:171], v[94:95], v[96:97]
	v_pk_add_f32 v[172:173], v[66:67], v[68:69]
	v_pk_add_f32 v[174:175], v[70:71], v[72:73]
	v_pk_add_f32 v[186:187], v[74:75], v[76:77]
	v_pk_add_f32 v[188:189], v[78:79], v[80:81]
	v_pk_add_f32 v[164:165], v[164:165], v[166:167]
	v_pk_add_f32 v[168:169], v[168:169], v[170:171]
	v_pk_add_f32 v[172:173], v[172:173], v[174:175]
	v_pk_add_f32 v[186:187], v[186:187], v[188:189]
	v_pk_add_f32 v[164:165], v[164:165], v[168:169]
	v_pk_add_f32 v[172:173], v[172:173], v[186:187]
	v_pk_add_f32 v[164:165], v[164:165], v[172:173]
	v_add_f32_e32 v164, v164, v165
	v_cvt_pk_bf16_f32 v66, v66, v67
	v_cvt_pk_bf16_f32 v67, v68, v69
	v_cvt_pk_bf16_f32 v68, v70, v71
	v_cvt_pk_bf16_f32 v69, v72, v73
	v_cvt_pk_bf16_f32 v70, v74, v75
	v_cvt_pk_bf16_f32 v71, v76, v77
	v_cvt_pk_bf16_f32 v72, v78, v79
	v_cvt_pk_bf16_f32 v73, v80, v81
	v_cvt_pk_bf16_f32 v74, v82, v83
	v_cvt_pk_bf16_f32 v75, v84, v85
	v_cvt_pk_bf16_f32 v76, v86, v87
	v_cvt_pk_bf16_f32 v77, v88, v89
	v_cvt_pk_bf16_f32 v78, v90, v91
	v_cvt_pk_bf16_f32 v79, v92, v93
	v_cvt_pk_bf16_f32 v80, v94, v95
	v_cvt_pk_bf16_f32 v81, v96, v97
	v_fmac_f32_e32 v164, v183, v0
	v_mov_b32_e32 v83, v164
	v_mov_b32_e32 v82, v162
	v_cmp_neq_f32_e32 vcc, 1.0, v0
	s_cbranch_vccz .LBB0_1179
	v_pk_mul_f32 v[64:65], v[64:65], v[0:1] op_sel_hi:[1,0]
	v_pk_mul_f32 v[62:63], v[62:63], v[0:1] op_sel_hi:[1,0]
	v_pk_mul_f32 v[60:61], v[60:61], v[0:1] op_sel_hi:[1,0]
	v_pk_mul_f32 v[58:59], v[58:59], v[0:1] op_sel_hi:[1,0]
	v_pk_mul_f32 v[56:57], v[56:57], v[0:1] op_sel_hi:[1,0]
	v_pk_mul_f32 v[54:55], v[54:55], v[0:1] op_sel_hi:[1,0]
	v_pk_mul_f32 v[52:53], v[52:53], v[0:1] op_sel_hi:[1,0]
	v_pk_mul_f32 v[50:51], v[50:51], v[0:1] op_sel_hi:[1,0]
	v_pk_mul_f32 v[48:49], v[48:49], v[0:1] op_sel_hi:[1,0]
	v_pk_mul_f32 v[46:47], v[46:47], v[0:1] op_sel_hi:[1,0]
	v_pk_mul_f32 v[44:45], v[44:45], v[0:1] op_sel_hi:[1,0]
	v_pk_mul_f32 v[42:43], v[42:43], v[0:1] op_sel_hi:[1,0]
	v_pk_mul_f32 v[40:41], v[40:41], v[0:1] op_sel_hi:[1,0]
	v_pk_mul_f32 v[38:39], v[38:39], v[0:1] op_sel_hi:[1,0]
	v_pk_mul_f32 v[36:37], v[36:37], v[0:1] op_sel_hi:[1,0]
	v_pk_mul_f32 v[34:35], v[34:35], v[0:1] op_sel_hi:[1,0]
	v_pk_mul_f32 v[32:33], v[32:33], v[0:1] op_sel_hi:[1,0]
	v_pk_mul_f32 v[30:31], v[30:31], v[0:1] op_sel_hi:[1,0]
	v_pk_mul_f32 v[28:29], v[28:29], v[0:1] op_sel_hi:[1,0]
	v_pk_mul_f32 v[26:27], v[26:27], v[0:1] op_sel_hi:[1,0]
	v_pk_mul_f32 v[24:25], v[24:25], v[0:1] op_sel_hi:[1,0]
	v_pk_mul_f32 v[22:23], v[22:23], v[0:1] op_sel_hi:[1,0]
	v_pk_mul_f32 v[20:21], v[20:21], v[0:1] op_sel_hi:[1,0]
	v_pk_mul_f32 v[18:19], v[18:19], v[0:1] op_sel_hi:[1,0]
	v_pk_mul_f32 v[16:17], v[16:17], v[0:1] op_sel_hi:[1,0]
	v_pk_mul_f32 v[14:15], v[14:15], v[0:1] op_sel_hi:[1,0]
	v_pk_mul_f32 v[12:13], v[12:13], v[0:1] op_sel_hi:[1,0]
	v_pk_mul_f32 v[10:11], v[10:11], v[0:1] op_sel_hi:[1,0]
	v_pk_mul_f32 v[8:9], v[8:9], v[0:1] op_sel_hi:[1,0]
	v_pk_mul_f32 v[6:7], v[6:7], v[0:1] op_sel_hi:[1,0]
	v_pk_mul_f32 v[4:5], v[4:5], v[0:1] op_sel_hi:[1,0]
	v_pk_mul_f32 v[2:3], v[2:3], v[0:1] op_sel_hi:[1,0]

.LBB0_1190:
	s_cmp_gt_i32 s14, s49
	s_cbranch_scc1 .LBB0_1194
	s_mul_i32 s15, s50, 0xa000
	s_add_i32 s15, s15, 0
	v_add_u32_e32 v0, s15, v186
	v_add_u32_e32 v6, v0, v188
	v_add_u32_e32 v14, v0, v189
	ds_read_b128 v[2:5], v6
	ds_read_b128 v[6:9], v6 offset:8192
	ds_read_b128 v[10:13], v14
	ds_read_b128 v[160:163], v14 offset:8192
	v_add_u32_e32 v14, v0, v190
	ds_read_b128 v[164:167], v14
	ds_read_b128 v[168:171], v14 offset:8192
	v_add_u32_e32 v14, v0, v191
	ds_read_b128 v[172:175], v14 offset:8192
	ds_read_b128 v[206:209], v14
	v_add_u32_e32 v14, s15, v177
	s_waitcnt lgkmcnt(0)
	v_mfma_f32_32x32x16_bf16 v[96:111], v[2:5], v[112:115], 0
	v_mfma_f32_32x32x16_bf16 v[80:95], v[6:9], v[112:115], 0
	v_mfma_f32_32x32x16_bf16 v[96:111], v[10:13], v[116:119], v[96:111]
	v_mfma_f32_32x32x16_bf16 v[80:95], v[160:163], v[116:119], v[80:95]
	v_mfma_f32_32x32x16_bf16 v[96:111], v[164:167], v[120:123], v[96:111]
	v_mfma_f32_32x32x16_bf16 v[80:95], v[168:171], v[120:123], v[80:95]
	v_mfma_f32_32x32x16_bf16 v[96:111], v[206:209], v[124:127], v[96:111]
	v_mfma_f32_32x32x16_bf16 v[80:95], v[172:175], v[124:127], v[80:95]
	v_add_u32_e32 v6, v0, v192
	v_add_u32_e32 v15, v0, v193
	ds_read_b128 v[2:5], v6
	ds_read_b128 v[6:9], v6 offset:8192
	ds_read_b128 v[10:13], v15
	ds_read_b128 v[160:163], v15 offset:8192
	v_add_u32_e32 v15, v0, v194
	v_add_u32_e32 v0, v0, v195
	ds_read_b128 v[164:167], v15
	ds_read_b128 v[168:171], v15 offset:8192
	ds_read_b128 v[172:175], v0 offset:8192
	ds_read_b128 v[206:209], v0
	s_waitcnt lgkmcnt(0)
	v_mfma_f32_32x32x16_bf16 v[96:111], v[2:5], v[128:131], v[96:111]
	v_mfma_f32_32x32x16_bf16 v[80:95], v[6:9], v[128:131], v[80:95]
	v_mfma_f32_32x32x16_bf16 v[96:111], v[10:13], v[132:135], v[96:111]
	v_mfma_f32_32x32x16_bf16 v[80:95], v[160:163], v[132:135], v[80:95]
	v_mfma_f32_32x32x16_bf16 v[96:111], v[164:167], v[136:139], v[96:111]
	v_mfma_f32_32x32x16_bf16 v[80:95], v[168:171], v[136:139], v[80:95]
	v_mfma_f32_32x32x16_bf16 v[96:111], v[206:209], v[140:143], v[96:111]
	v_mfma_f32_32x32x16_bf16 v[80:95], v[172:175], v[140:143], v[80:95]
	v_add_u32_e32 v0, v14, v196
	ds_read_b128 v[2:5], v0 offset:32768
	ds_read_b128 v[6:9], v0 offset:36864
	v_add_u32_e32 v0, v14, v197
	ds_read_b128 v[10:13], v0 offset:32768
	ds_read_b128 v[160:163], v0 offset:36864
	v_add_u32_e32 v0, v14, v198
	ds_read_b128 v[164:167], v0 offset:32768
	ds_read_b128 v[168:171], v0 offset:36864
	v_add_u32_e32 v0, v14, v199
	ds_read_b128 v[172:175], v0 offset:36864
	ds_read_b128 v[206:209], v0 offset:32768
	s_waitcnt lgkmcnt(0)
; __device__ __forceinline__ unsigned cvtpk(float lo, float hi) { unsigned r; asm("v_cvt_pk_bf16_f32 %0, %1, %2" : "=v"(r) : "v"(lo), "v"(hi)); return r; }
; __device__ __forceinline__ float max_x32(float v) { const unsigned u = __float_as_uint(v); auto r = __builtin_amdgcn_permlane32_swap(u, u, false, false); return fmaxf(__uint_as_float(r[0]), __uint_as_float(r[1])); }
; template <bool MASKED>
; __device__ __forceinline__ void softmax_tile(f32x16& s0, f32x16& s1, float& m, float& l, float& alpha, unsigned mlo, unsigned mhi, bf16x8 (&pk)[4]) {
;     ...
;     float mx = fmaxf(s0[0], s1[0]);
; #pragma unroll
;     for (int r = 1; r < 16; ++r) mx = fmaxf(mx, fmaxf(s0[r], s1[r]));
;     mx = max_x32(mx);
;     const float mn = fmaxf(m, mx);
;     alpha = __builtin_amdgcn_exp2f(m - mn); m = mn;
;     float sum = 0.f;
; #pragma unroll
;     for (int r = 0; r < 16; ++r) {
;         float p0 = __builtin_amdgcn_exp2f(s0[r] - mn), p1 = __builtin_amdgcn_exp2f(s1[r] - mn);
;         if (MASKED) { if (s0[r] <= -1e29f) p0 = 0.f; if (s1[r] <= -1e29f) p1 = 0.f; }
;         s0[r] = p0; s1[r] = p1; sum += p0 + p1;
;     }
;     l = l * alpha + sum;
; #pragma unroll
;     for (int k2 = 0; k2 < 2; ++k2) {
;         u32x4 a, b;
;         a.x = cvtpk(s0[8 * k2 + 0], s0[8 * k2 + 1]); a.y = cvtpk(s0[8 * k2 + 2], s0[8 * k2 + 3]); a.z = cvtpk(s0[8 * k2 + 4], s0[8 * k2 + 5]); a.w = cvtpk(s0[8 * k2 + 6], s0[8 * k2 + 7]);
;         b.x = cvtpk(s1[8 * k2 + 0], s1[8 * k2 + 1]); b.y = cvtpk(s1[8 * k2 + 2], s1[8 * k2 + 3]); b.z = cvtpk(s1[8 * k2 + 4], s1[8 * k2 + 5]); b.w = cvtpk(s1[8 * k2 + 6], s1[8 * k2 + 7]);
;         pk[k2] = __builtin_bit_cast(bf16x8, a); pk[2 + k2] = __builtin_bit_cast(bf16x8, b);
;     }
	v_mfma_f32_32x32x16_bf16 v[96:111], v[2:5], v[144:147], v[96:111]
	v_mfma_f32_32x32x16_bf16 v[80:95], v[6:9], v[144:147], v[80:95]
	v_mfma_f32_32x32x16_bf16 v[96:111], v[10:13], v[148:151], v[96:111]
	v_mfma_f32_32x32x16_bf16 v[80:95], v[160:163], v[148:151], v[80:95]
	v_mfma_f32_32x32x16_bf16 v[96:111], v[164:167], v[152:155], v[96:111]
	v_mfma_f32_32x32x16_bf16 v[80:95], v[168:171], v[152:155], v[80:95]
	v_mfma_f32_32x32x16_bf16 v[96:111], v[206:209], v[156:159], v[96:111]
	v_mfma_f32_32x32x16_bf16 v[80:95], v[172:175], v[156:159], v[80:95]
	s_nop 11
	v_max3_f32 v160, v96, v97, v98
	v_max3_f32 v161, v99, v100, v101
	v_max3_f32 v162, v102, v103, v104
	v_max3_f32 v163, v105, v106, v107
	v_max3_f32 v164, v108, v109, v110
	v_max3_f32 v165, v111, v80, v81
	v_max3_f32 v166, v82, v83, v84
	v_max3_f32 v167, v85, v86, v87
	v_max3_f32 v168, v88, v89, v90
	v_max3_f32 v169, v91, v92, v93
	v_max3_f32 v160, v160, v161, v162
	v_max3_f32 v163, v163, v164, v165
	v_max3_f32 v166, v166, v167, v168
	v_max3_f32 v169, v169, v94, v95
	v_max3_f32 v160, v160, v163, v166
	v_max_f32_e32 v160, v160, v169
	v_mov_b32_e32 v161, v160
	s_nop 1
	v_permlane32_swap_b32_e32 v160, v161
	v_max3_f32 v14, v235, v160, v161
	v_sub_f32_e32 v0, v235, v14
	v_pk_add_f32 v[96:97], v[96:97], v[14:15] op_sel_hi:[1,0] neg_lo:[0,1] neg_hi:[0,1]
	v_pk_add_f32 v[98:99], v[98:99], v[14:15] op_sel_hi:[1,0] neg_lo:[0,1] neg_hi:[0,1]
	v_pk_add_f32 v[100:101], v[100:101], v[14:15] op_sel_hi:[1,0] neg_lo:[0,1] neg_hi:[0,1]
	v_pk_add_f32 v[102:103], v[102:103], v[14:15] op_sel_hi:[1,0] neg_lo:[0,1] neg_hi:[0,1]
	v_pk_add_f32 v[104:105], v[104:105], v[14:15] op_sel_hi:[1,0] neg_lo:[0,1] neg_hi:[0,1]
	v_pk_add_f32 v[106:107], v[106:107], v[14:15] op_sel_hi:[1,0] neg_lo:[0,1] neg_hi:[0,1]
	v_pk_add_f32 v[108:109], v[108:109], v[14:15] op_sel_hi:[1,0] neg_lo:[0,1] neg_hi:[0,1]
	v_pk_add_f32 v[110:111], v[110:111], v[14:15] op_sel_hi:[1,0] neg_lo:[0,1] neg_hi:[0,1]
	v_pk_add_f32 v[80:81], v[80:81], v[14:15] op_sel_hi:[1,0] neg_lo:[0,1] neg_hi:[0,1]
	v_pk_add_f32 v[82:83], v[82:83], v[14:15] op_sel_hi:[1,0] neg_lo:[0,1] neg_hi:[0,1]
	v_pk_add_f32 v[84:85], v[84:85], v[14:15] op_sel_hi:[1,0] neg_lo:[0,1] neg_hi:[0,1]
	v_pk_add_f32 v[86:87], v[86:87], v[14:15] op_sel_hi:[1,0] neg_lo:[0,1] neg_hi:[0,1]
	v_pk_add_f32 v[88:89], v[88:89], v[14:15] op_sel_hi:[1,0] neg_lo:[0,1] neg_hi:[0,1]
	v_pk_add_f32 v[90:91], v[90:91], v[14:15] op_sel_hi:[1,0] neg_lo:[0,1] neg_hi:[0,1]
	v_pk_add_f32 v[92:93], v[92:93], v[14:15] op_sel_hi:[1,0] neg_lo:[0,1] neg_hi:[0,1]
	v_pk_add_f32 v[94:95], v[94:95], v[14:15] op_sel_hi:[1,0] neg_lo:[0,1] neg_hi:[0,1]
	v_exp_f32_e32 v0, v0
	v_exp_f32_e32 v96, v96
	v_exp_f32_e32 v97, v97
	v_exp_f32_e32 v98, v98
	v_exp_f32_e32 v99, v99
	v_exp_f32_e32 v100, v100
	v_exp_f32_e32 v101, v101
	v_exp_f32_e32 v102, v102
	v_exp_f32_e32 v103, v103
	v_exp_f32_e32 v104, v104
	v_exp_f32_e32 v105, v105
	v_exp_f32_e32 v106, v106
	v_exp_f32_e32 v107, v107
	v_exp_f32_e32 v108, v108
	v_exp_f32_e32 v109, v109
	v_exp_f32_e32 v110, v110
	v_exp_f32_e32 v111, v111
	v_exp_f32_e32 v80, v80
	v_exp_f32_e32 v81, v81
	v_exp_f32_e32 v82, v82
	v_exp_f32_e32 v83, v83
	v_exp_f32_e32 v84, v84
	v_exp_f32_e32 v85, v85
	v_exp_f32_e32 v86, v86
	v_exp_f32_e32 v87, v87
	v_exp_f32_e32 v88, v88
	v_exp_f32_e32 v89, v89
	v_exp_f32_e32 v90, v90
	v_exp_f32_e32 v91, v91
	v_exp_f32_e32 v92, v92
	v_exp_f32_e32 v93, v93
	v_exp_f32_e32 v94, v94
	v_exp_f32_e32 v95, v95
	v_pk_add_f32 v[160:161], v[96:97], v[98:99]
	v_pk_add_f32 v[162:163], v[100:101], v[102:103]
	v_pk_add_f32 v[164:165], v[104:105], v[106:107]
	v_pk_add_f32 v[166:167], v[108:109], v[110:111]
	v_pk_add_f32 v[168:169], v[80:81], v[82:83]
	v_pk_add_f32 v[170:171], v[84:85], v[86:87]
	v_pk_add_f32 v[172:173], v[88:89], v[90:91]
	v_pk_add_f32 v[174:175], v[92:93], v[94:95]
	v_pk_add_f32 v[160:161], v[160:161], v[162:163]
	v_pk_add_f32 v[164:165], v[164:165], v[166:167]
	v_pk_add_f32 v[168:169], v[168:169], v[170:171]
	v_pk_add_f32 v[172:173], v[172:173], v[174:175]
	v_pk_add_f32 v[160:161], v[160:161], v[164:165]
	v_pk_add_f32 v[168:169], v[168:169], v[172:173]
	v_pk_add_f32 v[160:161], v[160:161], v[168:169]
	v_add_f32_e32 v15, v160, v161
	v_cvt_pk_bf16_f32 v2, v80, v81
	v_cvt_pk_bf16_f32 v3, v82, v83
	v_cvt_pk_bf16_f32 v4, v84, v85
	v_cvt_pk_bf16_f32 v5, v86, v87
	v_cvt_pk_bf16_f32 v6, v88, v89
	v_cvt_pk_bf16_f32 v7, v90, v91
	v_cvt_pk_bf16_f32 v8, v92, v93
	v_cvt_pk_bf16_f32 v9, v94, v95
	v_cvt_pk_bf16_f32 v80, v104, v105
	v_cvt_pk_bf16_f32 v81, v106, v107
	v_cvt_pk_bf16_f32 v82, v108, v109
	v_cvt_pk_bf16_f32 v83, v110, v111
	v_cvt_pk_bf16_f32 v10, v96, v97
	v_cvt_pk_bf16_f32 v11, v98, v99
	v_cvt_pk_bf16_f32 v12, v100, v101
	v_cvt_pk_bf16_f32 v13, v102, v103
	v_fmac_f32_e32 v15, v234, v0
	v_cmp_neq_f32_e32 vcc, 1.0, v0
	s_cbranch_vccz .LBB0_1193
	v_pk_mul_f32 v[78:79], v[78:79], v[0:1] op_sel_hi:[1,0]
	v_pk_mul_f32 v[76:77], v[76:77], v[0:1] op_sel_hi:[1,0]
	v_pk_mul_f32 v[74:75], v[74:75], v[0:1] op_sel_hi:[1,0]
	v_pk_mul_f32 v[72:73], v[72:73], v[0:1] op_sel_hi:[1,0]
	v_pk_mul_f32 v[70:71], v[70:71], v[0:1] op_sel_hi:[1,0]
	v_pk_mul_f32 v[68:69], v[68:69], v[0:1] op_sel_hi:[1,0]
	v_pk_mul_f32 v[66:67], v[66:67], v[0:1] op_sel_hi:[1,0]
	v_pk_mul_f32 v[64:65], v[64:65], v[0:1] op_sel_hi:[1,0]
	v_pk_mul_f32 v[62:63], v[62:63], v[0:1] op_sel_hi:[1,0]
	v_pk_mul_f32 v[60:61], v[60:61], v[0:1] op_sel_hi:[1,0]
	v_pk_mul_f32 v[58:59], v[58:59], v[0:1] op_sel_hi:[1,0]
	v_pk_mul_f32 v[56:57], v[56:57], v[0:1] op_sel_hi:[1,0]
	v_pk_mul_f32 v[54:55], v[54:55], v[0:1] op_sel_hi:[1,0]
	v_pk_mul_f32 v[52:53], v[52:53], v[0:1] op_sel_hi:[1,0]
	v_pk_mul_f32 v[50:51], v[50:51], v[0:1] op_sel_hi:[1,0]
	v_pk_mul_f32 v[48:49], v[48:49], v[0:1] op_sel_hi:[1,0]
	v_pk_mul_f32 v[46:47], v[46:47], v[0:1] op_sel_hi:[1,0]
	v_pk_mul_f32 v[44:45], v[44:45], v[0:1] op_sel_hi:[1,0]
	v_pk_mul_f32 v[42:43], v[42:43], v[0:1] op_sel_hi:[1,0]
	v_pk_mul_f32 v[40:41], v[40:41], v[0:1] op_sel_hi:[1,0]
	v_pk_mul_f32 v[38:39], v[38:39], v[0:1] op_sel_hi:[1,0]
	v_pk_mul_f32 v[36:37], v[36:37], v[0:1] op_sel_hi:[1,0]
	v_pk_mul_f32 v[34:35], v[34:35], v[0:1] op_sel_hi:[1,0]
	v_pk_mul_f32 v[32:33], v[32:33], v[0:1] op_sel_hi:[1,0]
	v_pk_mul_f32 v[30:31], v[30:31], v[0:1] op_sel_hi:[1,0]
	v_pk_mul_f32 v[28:29], v[28:29], v[0:1] op_sel_hi:[1,0]
	v_pk_mul_f32 v[26:27], v[26:27], v[0:1] op_sel_hi:[1,0]
	v_pk_mul_f32 v[24:25], v[24:25], v[0:1] op_sel_hi:[1,0]
	v_pk_mul_f32 v[22:23], v[22:23], v[0:1] op_sel_hi:[1,0]
	v_pk_mul_f32 v[20:21], v[20:21], v[0:1] op_sel_hi:[1,0]
	v_pk_mul_f32 v[18:19], v[18:19], v[0:1] op_sel_hi:[1,0]
	v_pk_mul_f32 v[16:17], v[16:17], v[0:1] op_sel_hi:[1,0]
